# latent attention stack: QK-section VALU re-spaced across MFMA gaps + packed pk_fma split into scalar fmamk + self-max folds + counted per-MFMA lgkmcnt waits in the PV sections
# baseline (speedup 1.0000x reference)
.LBB0_709:
	s_add_i32 s20, s85, -3
	ds_read_b128 v[64:67], v204 offset:49152
	ds_read_b128 v[68:71], v204 offset:57344
	ds_read_b128 v[178:181], v207 offset:49152
	ds_read_b128 v[182:185], v207 offset:57344
	s_waitcnt lgkmcnt(3)
	v_mfma_f32_32x32x16_bf16 v[80:95], v[64:67], v[124:127], 0
	v_exp_f32_e32 v144, v158
	v_exp_f32_e32 v158, v159
	v_cvt_pk_bf16_f32 v162, v173, v175
	s_waitcnt lgkmcnt(2)
	v_mfma_f32_32x32x16_bf16 v[64:79], v[68:71], v[124:127], 0
	v_exp_f32_e32 v159, v160
	v_add_f32_e32 v160, 0, v216
	v_add_f32_e32 v160, v230, v160
	v_add_f32_e32 v160, v174, v160
	v_add_f32_e32 v160, v219, v160
	s_waitcnt lgkmcnt(1)
	v_mfma_f32_32x32x16_bf16 v[80:95], v[178:181], v[120:123], v[80:95]
	v_add_f32_e32 v160, v173, v160
	v_add_f32_e32 v160, v175, v160
	v_add_f32_e32 v160, v163, v160
	v_add_f32_e32 v160, v172, v160
	v_add_f32_e32 v160, v164, v160
	s_waitcnt lgkmcnt(0)
	v_mfma_f32_32x32x16_bf16 v[64:79], v[182:185], v[120:123], v[64:79]
	v_add_f32_e32 v160, v171, v160
	v_add_f32_e32 v160, v165, v160
	v_add_f32_e32 v160, v170, v160
	v_add_f32_e32 v160, v166, v160
	v_add_f32_e32 v160, v169, v160
	ds_read_b128 v[178:181], v209 offset:49152
	ds_read_b128 v[182:185], v209 offset:57344
	s_waitcnt lgkmcnt(1)
	v_mfma_f32_32x32x16_bf16 v[80:95], v[178:181], v[116:119], v[80:95]
	v_exp_f32_e32 v156, v156
	v_add_f32_e32 v160, v145, v160
	v_exp_f32_e32 v157, v157
	v_add_f32_e32 v160, v167, v160
	v_add_f32_e32 v160, v144, v160
	s_waitcnt lgkmcnt(0)
	v_mfma_f32_32x32x16_bf16 v[64:79], v[182:185], v[116:119], v[64:79]
	v_exp_f32_e32 v150, v150
	v_exp_f32_e32 v151, v151
	v_add_f32_e32 v160, v158, v160
	v_add_f32_e32 v160, v156, v160
	v_add_f32_e32 v160, v157, v160
	ds_read_b128 v[178:181], v205 offset:49152
	ds_read_b128 v[182:185], v205 offset:57344
	s_waitcnt lgkmcnt(1)
	v_mfma_f32_32x32x16_bf16 v[80:95], v[178:181], v[112:115], v[80:95]
	v_exp_f32_e32 v148, v148
	v_exp_f32_e32 v149, v149
	v_add_f32_e32 v160, v150, v160
	v_add_f32_e32 v160, v151, v160
	v_add_f32_e32 v160, v148, v160
	s_waitcnt lgkmcnt(0)
	v_mfma_f32_32x32x16_bf16 v[64:79], v[182:185], v[112:115], v[64:79]
	v_exp_f32_e32 v146, v146
	v_exp_f32_e32 v147, v147
	v_add_f32_e32 v160, v149, v160
	v_add_f32_e32 v160, v146, v160
	v_add_f32_e32 v160, v147, v160
	ds_read_b128 v[178:181], v206 offset:49152
	ds_read_b128 v[182:185], v206 offset:57344
	s_waitcnt lgkmcnt(1)
	v_mfma_f32_32x32x16_bf16 v[80:95], v[178:181], v[108:111], v[80:95]
	v_exp_f32_e32 v154, v154
	v_exp_f32_e32 v155, v155
	v_add_f32_e32 v160, v159, v160
	v_cvt_pk_bf16_f32 v163, v163, v172
	v_cvt_pk_bf16_f32 v164, v164, v171
	s_waitcnt lgkmcnt(0)
	v_mfma_f32_32x32x16_bf16 v[64:79], v[182:185], v[108:111], v[64:79]
	v_exp_f32_e32 v152, v152
	v_exp_f32_e32 v153, v153
	v_cvt_pk_bf16_f32 v165, v165, v170
	v_cvt_pk_bf16_f32 v166, v166, v169
	v_cvt_pk_bf16_f32 v167, v145, v167
	ds_read_b128 v[178:181], v208 offset:49152
	ds_read_b128 v[182:185], v208 offset:57344
	s_waitcnt lgkmcnt(1)
	v_mfma_f32_32x32x16_bf16 v[80:95], v[178:181], v[104:107], v[80:95]
	v_cvt_pk_bf16_f32 v170, v144, v158
	v_cvt_pk_bf16_f32 v171, v156, v157
	v_cvt_pk_bf16_f32 v172, v150, v151
	v_cvt_pk_bf16_f32 v173, v148, v149
	v_permlane32_swap_b32_e32 v164, v166
	s_waitcnt lgkmcnt(0)
	v_mfma_f32_32x32x16_bf16 v[64:79], v[182:185], v[104:107], v[64:79]
	v_permlane32_swap_b32_e32 v165, v167
	v_permlane32_swap_b32_e32 v170, v172
	v_permlane32_swap_b32_e32 v171, v173
	ds_read_b128 v[178:181], v210 offset:49152
	ds_read_b128 v[182:185], v210 offset:57344
	s_waitcnt lgkmcnt(1)
	v_mfma_f32_32x32x16_bf16 v[80:95], v[178:181], v[100:103], v[80:95]
	s_waitcnt lgkmcnt(0)
	v_mfma_f32_32x32x16_bf16 v[64:79], v[182:185], v[100:103], v[64:79]
	ds_read_b128 v[178:181], v211 offset:49152
	ds_read_b128 v[182:185], v211 offset:57344
	s_waitcnt lgkmcnt(1)
	v_mfma_f32_32x32x16_bf16 v[80:95], v[178:181], v[96:99], v[80:95]
	v_exp_f32_e32 v179, v161
	s_nop 0
	v_add_f32_e32 v160, v179, v160
	v_add_f32_e32 v160, v154, v160
	v_add_f32_e32 v160, v155, v160
	v_add_f32_e32 v160, v152, v160
	s_waitcnt lgkmcnt(0)
	v_mfma_f32_32x32x16_bf16 v[64:79], v[182:185], v[96:99], v[64:79]
	v_add_f32_e32 v213, v153, v160
	v_mov_b32_e32 v214, v213
	v_cvt_pk_bf16_f32 v160, v216, v230
	v_cvt_pk_bf16_f32 v161, v174, v219
	v_permlane32_swap_b32_e32 v213, v214
	v_permlane32_swap_b32_e32 v160, v162
	v_cvt_pk_bf16_f32 v178, v146, v147
	v_cvt_pk_bf16_f32 v179, v159, v179
	v_cvt_pk_bf16_f32 v180, v154, v155
	v_cvt_pk_bf16_f32 v181, v152, v153
	v_permlane32_swap_b32_e32 v161, v163
	v_permlane32_swap_b32_e32 v178, v180
	v_permlane32_swap_b32_e32 v179, v181
	s_cmp_lt_u32 s20, 6
	s_cselect_b64 s[4:5], -1, 0
	s_and_b64 s[18:19], s[4:5], exec
	s_cselect_b32 s16, 0, -8
	s_add_i32 s16, s16, s85
	s_add_i32 s16, s16, -1
	s_and_b64 s[4:5], s[4:5], exec
	s_cselect_b32 s19, s49, s43
	s_cselect_b32 s18, s48, s36
	s_cselect_b32 s21, s57, s52
	s_cselect_b32 s22, s56, s44
	s_lshl_b64 s[4:5], s[16:17], 16
	s_add_u32 s18, s18, s4
	s_addc_u32 s19, s19, s5
	s_add_u32 s4, s22, s4
	s_addc_u32 s5, s21, s5
	global_load_dwordx4 v[144:147], v222, s[4:5]
	global_load_dwordx4 v[148:151], v243, s[4:5]
	global_load_dwordx4 v[152:155], v222, s[18:19]
	global_load_dwordx4 v[156:159], v243, s[18:19]
	ds_read_b64_tr_b16 v[182:183], v199 offset:0
	ds_read_b64_tr_b16 v[184:185], v199 offset:0x800
	ds_read_b64_tr_b16 v[216:217], v199 offset:0x1000
	ds_read_b64_tr_b16 v[218:219], v199 offset:0x1800
	ds_read_b64_tr_b16 v[230:231], v199 offset:0x2000
	ds_read_b64_tr_b16 v[232:233], v199 offset:0x2800
	ds_read_b64_tr_b16 v[234:235], v199 offset:0x3000
	ds_read_b64_tr_b16 v[236:237], v199 offset:0x3800
	s_nop 0
	s_waitcnt lgkmcnt(6)
	v_mfma_f32_32x32x16_bf16 v[0:15], v[160:163], v[182:185], v[0:15]
	ds_read_b64_tr_b16 v[182:183], v199 offset:0x200
	ds_read_b64_tr_b16 v[184:185], v199 offset:0xa00
	s_waitcnt lgkmcnt(6)
	v_mfma_f32_32x32x16_bf16 v[0:15], v[164:167], v[216:219], v[0:15]
	ds_read_b64_tr_b16 v[216:217], v199 offset:0x1200
	ds_read_b64_tr_b16 v[218:219], v199 offset:0x1a00
	s_waitcnt lgkmcnt(6)
	v_mfma_f32_32x32x16_bf16 v[0:15], v[170:173], v[230:233], v[0:15]
	ds_read_b64_tr_b16 v[230:231], v199 offset:0x2200
	ds_read_b64_tr_b16 v[232:233], v199 offset:0x2a00
	s_waitcnt lgkmcnt(6)
	v_mfma_f32_32x32x16_bf16 v[0:15], v[178:181], v[234:237], v[0:15]
	ds_read_b64_tr_b16 v[234:235], v199 offset:0x3200
	ds_read_b64_tr_b16 v[236:237], v199 offset:0x3a00
	s_waitcnt lgkmcnt(6)
	v_mfma_f32_32x32x16_bf16 v[48:63], v[160:163], v[182:185], v[48:63]
	ds_read_b64_tr_b16 v[182:183], v199 offset:0x400
	ds_read_b64_tr_b16 v[184:185], v199 offset:0xc00
	s_waitcnt lgkmcnt(6)
	v_mfma_f32_32x32x16_bf16 v[48:63], v[164:167], v[216:219], v[48:63]
	ds_read_b64_tr_b16 v[216:217], v199 offset:0x1400
	ds_read_b64_tr_b16 v[218:219], v199 offset:0x1c00
	s_waitcnt lgkmcnt(6)
	v_mfma_f32_32x32x16_bf16 v[48:63], v[170:173], v[230:233], v[48:63]
	ds_read_b64_tr_b16 v[230:231], v199 offset:0x2400
	ds_read_b64_tr_b16 v[232:233], v199 offset:0x2c00
	s_waitcnt lgkmcnt(6)
	v_mfma_f32_32x32x16_bf16 v[48:63], v[178:181], v[234:237], v[48:63]
	ds_read_b64_tr_b16 v[234:235], v199 offset:0x3400
	ds_read_b64_tr_b16 v[236:237], v199 offset:0x3c00
	s_waitcnt lgkmcnt(6)
	v_mfma_f32_32x32x16_bf16 v[32:47], v[160:163], v[182:185], v[32:47]
	ds_read_b64_tr_b16 v[182:183], v199 offset:0x600
	ds_read_b64_tr_b16 v[184:185], v199 offset:0xe00
	s_waitcnt lgkmcnt(6)
	v_mfma_f32_32x32x16_bf16 v[32:47], v[164:167], v[216:219], v[32:47]
	ds_read_b64_tr_b16 v[216:217], v199 offset:0x1600
	ds_read_b64_tr_b16 v[218:219], v199 offset:0x1e00
	s_waitcnt lgkmcnt(6)
	v_mfma_f32_32x32x16_bf16 v[32:47], v[170:173], v[230:233], v[32:47]
	ds_read_b64_tr_b16 v[230:231], v199 offset:0x2600
	ds_read_b64_tr_b16 v[232:233], v199 offset:0x2e00
	s_waitcnt lgkmcnt(6)
	v_mfma_f32_32x32x16_bf16 v[32:47], v[178:181], v[234:237], v[32:47]
	ds_read_b64_tr_b16 v[234:235], v199 offset:0x3600
	ds_read_b64_tr_b16 v[236:237], v199 offset:0x3e00
	s_waitcnt lgkmcnt(6)
	v_mfma_f32_32x32x16_bf16 v[16:31], v[160:163], v[182:185], v[16:31]
	v_max_f32_e32 v160, v81, v80
	v_max3_f32 v160, v160, v82, v83
	v_max3_f32 v160, v160, v84, v85
	v_max3_f32 v160, v160, v86, v87
	v_max3_f32 v160, v160, v88, v89
	v_max3_f32 v160, v160, v90, v91
	v_max3_f32 v160, v160, v92, v93
	s_waitcnt lgkmcnt(4)
	v_mfma_f32_32x32x16_bf16 v[16:31], v[164:167], v[216:219], v[16:31]
	v_max3_f32 v160, v160, v94, v95
	v_max3_f32 v160, v160, v64, v65
	v_max3_f32 v160, v160, v66, v67
	v_max3_f32 v160, v160, v68, v69
	v_max3_f32 v160, v160, v70, v71
	v_max3_f32 v160, v160, v72, v73
	v_max3_f32 v160, v160, v74, v75
	v_max3_f32 v160, v160, v76, v77
	s_waitcnt lgkmcnt(2)
	v_mfma_f32_32x32x16_bf16 v[16:31], v[170:173], v[230:233], v[16:31]
	v_max3_f32 v160, v160, v78, v79
	v_mov_b32_e32 v161, v160
	s_nop 1
	v_permlane32_swap_b32_e32 v160, v161
	v_max_f32_e32 v160, v161, v160
	v_sub_f32_e32 v161, v160, v168
	v_cmp_ge_f32_e32 vcc, s14, v161
	v_max_f32_e32 v160, v168, v160
	s_waitcnt lgkmcnt(0)
	v_mfma_f32_32x32x16_bf16 v[16:31], v[178:181], v[234:237], v[16:31]
	v_sub_f32_e32 v161, v168, v160
	v_mul_f32_e32 v161, 0x3e0293ee, v161
	v_exp_f32_e32 v161, v161
	s_cmp_eq_u64 vcc, exec
	s_cselect_b64 s[4:5], -1, 0
	s_barrier
	s_waitcnt vmcnt(4)
	v_cndmask_b32_e64 v215, v161, 1.0, s[4:5]
	v_cmp_gt_f32_e32 vcc, 1.0, v215
	s_waitcnt vmcnt(4)
	ds_write_b128 v200, v[128:131]
	ds_write_b128 v201, v[132:135]
	ds_write_b128 v202, v[136:139] offset:32768
	ds_write_b128 v203, v[140:143] offset:32768
	s_cbranch_vccz .LBB0_713
	s_and_saveexec_b64 s[18:19], s[2:3]
	ds_write_b32 v189, v215 offset:128
	s_or_b64 exec, exec, s[18:19]
	s_waitcnt lgkmcnt(0)
	v_add_u32_e32 v161, v191, v190
	ds_read_b128 v[162:165], v161 offset:224
	ds_read_b128 v[170:173], v161 offset:192
	ds_read_b128 v[178:181], v161 offset:160
	ds_read_b128 v[182:185], v161 offset:128
	s_waitcnt lgkmcnt(3)
	v_pk_mul_f32 v[12:13], v[12:13], v[162:163]
	s_waitcnt lgkmcnt(2)
	v_pk_mul_f32 v[8:9], v[8:9], v[170:171]
	s_waitcnt lgkmcnt(1)
	v_pk_mul_f32 v[4:5], v[4:5], v[178:179]
	v_pk_mul_f32 v[14:15], v[14:15], v[164:165]
	v_pk_mul_f32 v[10:11], v[10:11], v[172:173]
	v_pk_mul_f32 v[6:7], v[6:7], v[180:181]
	s_waitcnt lgkmcnt(0)
	v_pk_mul_f32 v[2:3], v[2:3], v[184:185]
	v_pk_mul_f32 v[0:1], v[0:1], v[182:183]
	v_pk_mul_f32 v[60:61], v[60:61], v[162:163]
	v_pk_mul_f32 v[56:57], v[56:57], v[170:171]
	v_pk_mul_f32 v[52:53], v[52:53], v[178:179]
	v_pk_mul_f32 v[62:63], v[62:63], v[164:165]
	v_pk_mul_f32 v[58:59], v[58:59], v[172:173]
	v_pk_mul_f32 v[54:55], v[54:55], v[180:181]
	v_pk_mul_f32 v[50:51], v[50:51], v[184:185]
	v_pk_mul_f32 v[48:49], v[48:49], v[182:183]
	v_pk_mul_f32 v[44:45], v[44:45], v[162:163]
	v_pk_mul_f32 v[40:41], v[40:41], v[170:171]
	v_pk_mul_f32 v[36:37], v[36:37], v[178:179]
	v_pk_mul_f32 v[46:47], v[46:47], v[164:165]
	v_pk_mul_f32 v[42:43], v[42:43], v[172:173]
	v_pk_mul_f32 v[38:39], v[38:39], v[180:181]
	v_pk_mul_f32 v[34:35], v[34:35], v[184:185]
	v_pk_mul_f32 v[32:33], v[32:33], v[182:183]
	v_pk_mul_f32 v[28:29], v[28:29], v[162:163]
	v_pk_mul_f32 v[24:25], v[24:25], v[170:171]
	v_pk_mul_f32 v[20:21], v[20:21], v[178:179]
	v_pk_mul_f32 v[30:31], v[30:31], v[164:165]
	v_pk_mul_f32 v[26:27], v[26:27], v[172:173]
	v_pk_mul_f32 v[22:23], v[22:23], v[180:181]
	v_pk_mul_f32 v[18:19], v[18:19], v[184:185]
	v_pk_mul_f32 v[16:17], v[16:17], v[182:183]

.LBB0_715:
	ds_read_b64_tr_b16 v[178:179], v198 offset:0
	ds_read_b64_tr_b16 v[180:181], v198 offset:0x800
	ds_read_b64_tr_b16 v[182:183], v198 offset:0x1000
	ds_read_b64_tr_b16 v[184:185], v198 offset:0x1800
	ds_read_b64_tr_b16 v[230:231], v198 offset:0x2000
	ds_read_b64_tr_b16 v[232:233], v198 offset:0x2800
	ds_read_b64_tr_b16 v[234:235], v198 offset:0x3000
	ds_read_b64_tr_b16 v[236:237], v198 offset:0x3800
	s_nop 0
	s_waitcnt lgkmcnt(6)
	v_mfma_f32_32x32x16_bf16 v[0:15], v[160:163], v[178:181], v[0:15]
	ds_read_b64_tr_b16 v[178:179], v198 offset:0x200
	ds_read_b64_tr_b16 v[180:181], v198 offset:0xa00
	s_waitcnt lgkmcnt(6)
	v_mfma_f32_32x32x16_bf16 v[0:15], v[164:167], v[182:185], v[0:15]
	ds_read_b64_tr_b16 v[182:183], v198 offset:0x1200
	ds_read_b64_tr_b16 v[184:185], v198 offset:0x1a00
	s_waitcnt lgkmcnt(6)
	v_mfma_f32_32x32x16_bf16 v[0:15], v[168:171], v[230:233], v[0:15]
	ds_read_b64_tr_b16 v[230:231], v198 offset:0x2200
	ds_read_b64_tr_b16 v[232:233], v198 offset:0x2a00
	s_waitcnt lgkmcnt(6)
	v_mfma_f32_32x32x16_bf16 v[0:15], v[172:175], v[234:237], v[0:15]
	ds_read_b64_tr_b16 v[234:235], v198 offset:0x3200
	ds_read_b64_tr_b16 v[236:237], v198 offset:0x3a00
	s_waitcnt lgkmcnt(6)
	v_mfma_f32_32x32x16_bf16 v[48:63], v[160:163], v[178:181], v[48:63]
	ds_read_b64_tr_b16 v[178:179], v198 offset:0x400
	ds_read_b64_tr_b16 v[180:181], v198 offset:0xc00
	s_waitcnt lgkmcnt(6)
	v_mfma_f32_32x32x16_bf16 v[48:63], v[164:167], v[182:185], v[48:63]
	ds_read_b64_tr_b16 v[182:183], v198 offset:0x1400
	ds_read_b64_tr_b16 v[184:185], v198 offset:0x1c00
	s_waitcnt lgkmcnt(6)
	v_mfma_f32_32x32x16_bf16 v[48:63], v[168:171], v[230:233], v[48:63]
	ds_read_b64_tr_b16 v[230:231], v198 offset:0x2400
	ds_read_b64_tr_b16 v[232:233], v198 offset:0x2c00
	s_waitcnt lgkmcnt(6)
	v_mfma_f32_32x32x16_bf16 v[48:63], v[172:175], v[234:237], v[48:63]
	ds_read_b64_tr_b16 v[234:235], v198 offset:0x3400
	ds_read_b64_tr_b16 v[236:237], v198 offset:0x3c00
	s_waitcnt lgkmcnt(6)
	v_mfma_f32_32x32x16_bf16 v[32:47], v[160:163], v[178:181], v[32:47]
	ds_read_b64_tr_b16 v[178:179], v198 offset:0x600
	ds_read_b64_tr_b16 v[180:181], v198 offset:0xe00
	s_waitcnt lgkmcnt(6)
	v_mfma_f32_32x32x16_bf16 v[32:47], v[164:167], v[182:185], v[32:47]
	ds_read_b64_tr_b16 v[182:183], v198 offset:0x1600
	ds_read_b64_tr_b16 v[184:185], v198 offset:0x1e00
	s_waitcnt lgkmcnt(6)
	v_mfma_f32_32x32x16_bf16 v[32:47], v[168:171], v[230:233], v[32:47]
	ds_read_b64_tr_b16 v[230:231], v198 offset:0x2600
	ds_read_b64_tr_b16 v[232:233], v198 offset:0x2e00
	s_waitcnt lgkmcnt(6)
	v_mfma_f32_32x32x16_bf16 v[32:47], v[172:175], v[234:237], v[32:47]
	ds_read_b64_tr_b16 v[234:235], v198 offset:0x3600
	ds_read_b64_tr_b16 v[236:237], v198 offset:0x3e00
	s_waitcnt lgkmcnt(6)
	v_mfma_f32_32x32x16_bf16 v[16:31], v[160:163], v[178:181], v[16:31]
	v_max_f32_e32 v160, v81, v80
	v_max3_f32 v160, v160, v82, v83
	v_max3_f32 v160, v160, v84, v85
	v_max3_f32 v160, v160, v86, v87
	v_max3_f32 v160, v160, v88, v89
	v_max3_f32 v160, v160, v90, v91
	v_max3_f32 v160, v160, v92, v93
	s_waitcnt lgkmcnt(4)
	v_mfma_f32_32x32x16_bf16 v[16:31], v[164:167], v[182:185], v[16:31]
	v_max3_f32 v160, v160, v94, v95
	v_max3_f32 v160, v160, v64, v65
	v_max3_f32 v160, v160, v66, v67
	v_max3_f32 v160, v160, v68, v69
	v_max3_f32 v160, v160, v70, v71
	v_max3_f32 v160, v160, v72, v73
	v_max3_f32 v160, v160, v74, v75
	v_max3_f32 v160, v160, v76, v77
	s_waitcnt lgkmcnt(2)
	v_mfma_f32_32x32x16_bf16 v[16:31], v[168:171], v[230:233], v[16:31]
	v_max3_f32 v160, v160, v78, v79
	v_mov_b32_e32 v161, v160
	s_nop 1
	v_permlane32_swap_b32_e32 v160, v161
	v_max_f32_e32 v160, v161, v160
	v_sub_f32_e32 v161, v160, v216
	v_cmp_ge_f32_e32 vcc, s14, v161
	v_max_f32_e32 v160, v216, v160
	s_waitcnt lgkmcnt(0)
	v_mfma_f32_32x32x16_bf16 v[16:31], v[172:175], v[234:237], v[16:31]
	v_sub_f32_e32 v161, v216, v160
	v_mul_f32_e32 v161, 0x3e0293ee, v161
	v_exp_f32_e32 v161, v161
	s_cmp_eq_u64 vcc, exec
	s_cselect_b64 s[4:5], -1, 0
	s_barrier
	s_waitcnt vmcnt(4)
	v_cndmask_b32_e64 v162, v161, 1.0, s[4:5]
	v_cmp_gt_f32_e32 vcc, 1.0, v162
	s_waitcnt vmcnt(3)
	ds_write_b128 v200, v[144:147] offset:16384
	s_waitcnt vmcnt(2)
	ds_write_b128 v201, v[148:151] offset:16384
	s_waitcnt vmcnt(1)
	ds_write_b128 v202, v[152:155] offset:49152
	s_waitcnt vmcnt(0)
	ds_write_b128 v203, v[156:159] offset:49152
	s_cbranch_vccz .LBB0_719
	s_and_saveexec_b64 s[18:19], s[2:3]
	ds_write_b32 v189, v162 offset:128
	s_or_b64 exec, exec, s[18:19]
	s_waitcnt lgkmcnt(0)
	v_add_u32_e32 v156, v191, v190
	ds_read_b128 v[144:147], v156 offset:224
	ds_read_b128 v[148:151], v156 offset:192
	ds_read_b128 v[152:155], v156 offset:160
	ds_read_b128 v[156:159], v156 offset:128
	s_waitcnt lgkmcnt(3)
	v_pk_mul_f32 v[12:13], v[12:13], v[144:145]
	s_waitcnt lgkmcnt(2)
	v_pk_mul_f32 v[8:9], v[8:9], v[148:149]
	s_waitcnt lgkmcnt(1)
	v_pk_mul_f32 v[4:5], v[4:5], v[152:153]
	v_pk_mul_f32 v[14:15], v[14:15], v[146:147]
	v_pk_mul_f32 v[10:11], v[10:11], v[150:151]
	v_pk_mul_f32 v[6:7], v[6:7], v[154:155]
	s_waitcnt lgkmcnt(0)
	v_pk_mul_f32 v[2:3], v[2:3], v[158:159]
	v_pk_mul_f32 v[0:1], v[0:1], v[156:157]
	v_pk_mul_f32 v[60:61], v[60:61], v[144:145]
	v_pk_mul_f32 v[56:57], v[56:57], v[148:149]
	v_pk_mul_f32 v[52:53], v[52:53], v[152:153]
	v_pk_mul_f32 v[62:63], v[62:63], v[146:147]
	v_pk_mul_f32 v[58:59], v[58:59], v[150:151]
	v_pk_mul_f32 v[54:55], v[54:55], v[154:155]
	v_pk_mul_f32 v[50:51], v[50:51], v[158:159]
	v_pk_mul_f32 v[48:49], v[48:49], v[156:157]
	v_pk_mul_f32 v[44:45], v[44:45], v[144:145]
	v_pk_mul_f32 v[40:41], v[40:41], v[148:149]
	v_pk_mul_f32 v[36:37], v[36:37], v[152:153]
	v_pk_mul_f32 v[46:47], v[46:47], v[146:147]
	v_pk_mul_f32 v[42:43], v[42:43], v[150:151]
	v_pk_mul_f32 v[38:39], v[38:39], v[154:155]
	v_pk_mul_f32 v[34:35], v[34:35], v[158:159]
	v_pk_mul_f32 v[32:33], v[32:33], v[156:157]
	v_pk_mul_f32 v[28:29], v[28:29], v[144:145]
	v_pk_mul_f32 v[24:25], v[24:25], v[148:149]
	v_pk_mul_f32 v[20:21], v[20:21], v[152:153]
	v_pk_mul_f32 v[30:31], v[30:31], v[146:147]
	v_pk_mul_f32 v[26:27], v[26:27], v[150:151]
	v_pk_mul_f32 v[22:23], v[22:23], v[154:155]
	v_pk_mul_f32 v[18:19], v[18:19], v[158:159]
	v_pk_mul_f32 v[16:17], v[16:17], v[156:157]
